# diff attention loop edge: two 22-term serial v_add_f32 chains and 11 serial v_pk_add_f32 replaced by 4-way interleaved partial sums and a depth-5 pair tree (same f32 terms)
# speedup vs baseline: 1.0101x; 1.0101x over previous
.LBB0_769:
	v_add_f32_e32 v76, v175, v181
	v_add_f32_e32 v77, v96, v97
	v_add_f32_e32 v78, v98, v99
	v_add_f32_e32 v79, v100, v101
	v_add_f32_e32 v76, v102, v76
	v_add_f32_e32 v77, v103, v77
	v_add_f32_e32 v78, v104, v78
	v_add_f32_e32 v79, v105, v79
	v_add_f32_e32 v76, v106, v76
	v_add_f32_e32 v77, v107, v77
	v_add_f32_e32 v78, v108, v78
	v_add_f32_e32 v79, v109, v79
	v_add_f32_e32 v76, v183, v76
	v_add_f32_e32 v77, v184, v77
	v_add_f32_e32 v78, v185, v78
	v_add_f32_e32 v79, v186, v79
	v_add_f32_e32 v76, v187, v76
	v_add_f32_e32 v77, v188, v77
	v_add_f32_e32 v76, v76, v77
	v_add_f32_e32 v78, v78, v79
	v_add_f32_e32 v67, v67, v76
	s_nop 0
	v_add_f32_e32 v67, v67, v78
	s_add_i32 s4, s4, 64
	s_mov_b64 s[0:1], 0x80
	v_add_f32_e32 v76, v110, v111
	v_add_f32_e32 v77, v112, v113
	v_add_f32_e32 v78, v114, v115
	v_add_f32_e32 v79, v116, v117
	v_add_f32_e32 v76, v118, v76
	v_add_f32_e32 v77, v119, v77
	v_add_f32_e32 v78, v120, v78
	v_add_f32_e32 v79, v121, v79
	v_add_f32_e32 v76, v122, v76
	v_add_f32_e32 v77, v123, v77
	v_add_f32_e32 v78, v124, v78
	v_add_f32_e32 v79, v125, v79
	v_add_f32_e32 v76, v189, v76
	v_add_f32_e32 v77, v237, v77
	v_add_f32_e32 v78, v238, v78
	v_add_f32_e32 v79, v239, v79
	v_add_f32_e32 v76, v240, v76
	v_add_f32_e32 v77, v241, v77
	v_add_f32_e32 v76, v76, v77
	v_add_f32_e32 v78, v78, v79
	v_add_f32_e32 v66, v66, v76
	s_nop 0
	v_add_f32_e32 v66, v66, v78
	s_add_i32 s5, s5, 1
	v_lshl_add_u64 v[166:167], v[166:167], 0, s[0:1]
	v_lshl_add_u64 v[168:169], v[168:169], 0, s[0:1]
	s_cmpk_lg_i32 s4, 0x1100
	v_pk_add_f32 v[76:77], v[86:87], v[84:85]
	v_pk_add_f32 v[78:79], v[82:83], v[80:81]
	v_pk_add_f32 v[64:65], v[64:65], v[66:67]
	v_pk_add_f32 v[76:77], v[76:77], v[72:73]
	v_pk_add_f32 v[78:79], v[78:79], v[74:75]
	s_waitcnt lgkmcnt(0)
	v_pk_add_f32 v[76:77], v[76:77], v[70:71]
	v_pk_add_f32 v[78:79], v[78:79], v[68:69]
	s_barrier
	v_pk_add_f32 v[64:65], v[64:65], v[76:77]
	s_nop 0
	v_pk_add_f32 v[64:65], v[64:65], v[78:79]
	s_nop 0
	v_pk_add_f32 v[160:161], v[160:161], v[64:65]
	s_cbranch_scc0 .LBB0_774
